# P0: adaLN GEMV loads issued up front (64 in flight per wave, 40 before the silu staging), b_ada/gain prefetched, w_in conversion software-pipelined across items; bit-identical math
# speedup vs baseline: 1.0053x; 1.0053x over previous
.LBB0_13:
	v_lshlrev_b32_e32 v34, 2, v0
	v_mov_b32_e32 v35, 0
	v_lshl_add_u64 v[2:3], s[38:39], 0, v[34:35]
	global_load_dword v8, v34, s[38:39]
	global_load_dword v9, v34, s[38:39] offset:2048
	v_add_co_u32_e32 v4, vcc, 0x1000, v2
	s_movk_i32 s1, 0x6000
	s_nop 0
	v_addc_co_u32_e32 v5, vcc, 0, v3, vcc
	global_load_dword v10, v[4:5], off
	global_load_dword v11, v[4:5], off offset:2048
	v_add_co_u32_e32 v4, vcc, 0x2000, v2
	s_lshl_b32 s6, s0, 5
	s_nop 0
	v_addc_co_u32_e32 v5, vcc, 0, v3, vcc
	global_load_dword v12, v[4:5], off
	global_load_dword v13, v[4:5], off offset:2048
	v_add_co_u32_e32 v4, vcc, 0x3000, v2
	s_ashr_i32 s7, s6, 31
	s_nop 0
	v_addc_co_u32_e32 v5, vcc, 0, v3, vcc
	global_load_dword v14, v[4:5], off
	global_load_dword v15, v[4:5], off offset:2048
	v_add_co_u32_e32 v4, vcc, 0x4000, v2
	v_and_b32_e32 v48, 31, v0
	s_nop 0
	v_addc_co_u32_e32 v5, vcc, 0, v3, vcc
	global_load_dword v16, v[4:5], off
	global_load_dword v17, v[4:5], off offset:2048
	v_add_co_u32_e32 v4, vcc, 0x5000, v2
	v_lshlrev_b32_e32 v34, 2, v48
	s_nop 0
	v_addc_co_u32_e32 v5, vcc, 0, v3, vcc
	global_load_dword v18, v[4:5], off
	v_add_co_u32_e32 v6, vcc, 0x6000, v2
	global_load_dword v19, v[4:5], off offset:2048
	s_nop 0
	v_addc_co_u32_e32 v7, vcc, 0, v3, vcc
	global_load_dword v20, v[6:7], off
	v_add_co_u32_e32 v2, vcc, 0x7000, v2
	global_load_dword v6, v[6:7], off offset:2048
	s_nop 0
	v_addc_co_u32_e32 v3, vcc, 0, v3, vcc
	global_load_dword v7, v[2:3], off
	s_mov_b64 s[38:39], 0
	global_load_dword v2, v[2:3], off offset:2048
	v_lshl_add_u32 v3, v0, 5, 0
	v_add_u32_e32 v21, 0x4000, v3
	v_mov_b32_e32 v4, s40
	v_mov_b32_e32 v5, s41
	v_lshrrev_b32_e32 v244, 5, v1
	v_lshl_or_b32 v244, s99, 7, v244
	s_movk_i32 s32, 0x6000
	v_or_b32_e32 v245, s6, v48
	v_mad_u64_u32 v[246:247], s[96:97], v244, s32, v[4:5]
	v_lshlrev_b32_e32 v248, 2, v245
	v_and_b32_e32 v245, 0x3ff, v245
	v_lshl_add_u64 v[246:247], s[6:7], 2, v[246:247]
	v_lshlrev_b32_e32 v245, 2, v245
	v_lshl_add_u64 v[240:241], v[246:247], 0, v[34:35]
	s_ashr_i32 s32, s0, 5
	v_readlane_b32 s96, v250, 0
	v_readlane_b32 s97, v250, 1
	s_nop 3
	s_cmp_eq_u32 s32, 4
	s_cselect_b32 s96, s22, s96
	s_cselect_b32 s97, s23, s97
	s_cmp_eq_u32 s32, 2
	s_cselect_b32 s96, s46, s96
	s_cselect_b32 s97, s47, s97
	s_cmp_eq_u32 s32, 1
	s_cselect_b32 s96, s44, s96
	s_cselect_b32 s97, s45, s97
	global_load_dword v242, v248, s[42:43]
	global_load_dword v243, v245, s[96:97]
	s_nop 1
	s_mov_b32 s96, 0xc000
	s_mov_b32 s97, 0
	global_load_dword v176, v[240:241], off nt
	v_lshl_add_u64 v[240:241], v[240:241], 0, s[96:97]
	global_load_dword v177, v[240:241], off nt
	v_lshl_add_u64 v[240:241], v[240:241], 0, s[96:97]
	global_load_dword v178, v[240:241], off nt
	v_lshl_add_u64 v[240:241], v[240:241], 0, s[96:97]
	global_load_dword v179, v[240:241], off nt
	v_lshl_add_u64 v[240:241], v[240:241], 0, s[96:97]
	global_load_dword v180, v[240:241], off nt
	v_lshl_add_u64 v[240:241], v[240:241], 0, s[96:97]
	global_load_dword v181, v[240:241], off nt
	v_lshl_add_u64 v[240:241], v[240:241], 0, s[96:97]
	global_load_dword v182, v[240:241], off nt
	v_lshl_add_u64 v[240:241], v[240:241], 0, s[96:97]
	global_load_dword v183, v[240:241], off nt
	v_lshl_add_u64 v[240:241], v[240:241], 0, s[96:97]
	global_load_dword v184, v[240:241], off nt
	v_lshl_add_u64 v[240:241], v[240:241], 0, s[96:97]
	global_load_dword v185, v[240:241], off nt
	v_lshl_add_u64 v[240:241], v[240:241], 0, s[96:97]
	global_load_dword v186, v[240:241], off nt
	v_lshl_add_u64 v[240:241], v[240:241], 0, s[96:97]
	global_load_dword v187, v[240:241], off nt
	v_lshl_add_u64 v[240:241], v[240:241], 0, s[96:97]
	global_load_dword v188, v[240:241], off nt
	v_lshl_add_u64 v[240:241], v[240:241], 0, s[96:97]
	global_load_dword v189, v[240:241], off nt
	v_lshl_add_u64 v[240:241], v[240:241], 0, s[96:97]
	global_load_dword v190, v[240:241], off nt
	v_lshl_add_u64 v[240:241], v[240:241], 0, s[96:97]
	global_load_dword v191, v[240:241], off nt
	v_lshl_add_u64 v[240:241], v[240:241], 0, s[96:97]
	global_load_dword v192, v[240:241], off nt
	v_lshl_add_u64 v[240:241], v[240:241], 0, s[96:97]
	global_load_dword v193, v[240:241], off nt
	v_lshl_add_u64 v[240:241], v[240:241], 0, s[96:97]
	global_load_dword v194, v[240:241], off nt
	v_lshl_add_u64 v[240:241], v[240:241], 0, s[96:97]
	global_load_dword v195, v[240:241], off nt
	v_lshl_add_u64 v[240:241], v[240:241], 0, s[96:97]
	global_load_dword v196, v[240:241], off nt
	v_lshl_add_u64 v[240:241], v[240:241], 0, s[96:97]
	global_load_dword v197, v[240:241], off nt
	v_lshl_add_u64 v[240:241], v[240:241], 0, s[96:97]
	global_load_dword v198, v[240:241], off nt
	v_lshl_add_u64 v[240:241], v[240:241], 0, s[96:97]
	global_load_dword v199, v[240:241], off nt
	v_lshl_add_u64 v[240:241], v[240:241], 0, s[96:97]
	global_load_dword v200, v[240:241], off nt
	v_lshl_add_u64 v[240:241], v[240:241], 0, s[96:97]
	global_load_dword v201, v[240:241], off nt
	v_lshl_add_u64 v[240:241], v[240:241], 0, s[96:97]
	global_load_dword v202, v[240:241], off nt
	v_lshl_add_u64 v[240:241], v[240:241], 0, s[96:97]
	global_load_dword v203, v[240:241], off nt
	v_lshl_add_u64 v[240:241], v[240:241], 0, s[96:97]
	global_load_dword v204, v[240:241], off nt
	v_lshl_add_u64 v[240:241], v[240:241], 0, s[96:97]
	global_load_dword v205, v[240:241], off nt
	v_lshl_add_u64 v[240:241], v[240:241], 0, s[96:97]
	global_load_dword v206, v[240:241], off nt
	v_lshl_add_u64 v[240:241], v[240:241], 0, s[96:97]
	global_load_dword v207, v[240:241], off nt
	v_lshl_add_u64 v[240:241], v[240:241], 0, s[96:97]
	global_load_dword v208, v[240:241], off nt
	v_lshl_add_u64 v[240:241], v[240:241], 0, s[96:97]
	global_load_dword v209, v[240:241], off nt
	v_lshl_add_u64 v[240:241], v[240:241], 0, s[96:97]
	global_load_dword v210, v[240:241], off nt
	v_lshl_add_u64 v[240:241], v[240:241], 0, s[96:97]
	global_load_dword v211, v[240:241], off nt
	v_lshl_add_u64 v[240:241], v[240:241], 0, s[96:97]
	global_load_dword v212, v[240:241], off nt
	v_lshl_add_u64 v[240:241], v[240:241], 0, s[96:97]
	global_load_dword v213, v[240:241], off nt
	v_lshl_add_u64 v[240:241], v[240:241], 0, s[96:97]
	global_load_dword v214, v[240:241], off nt
	v_lshl_add_u64 v[240:241], v[240:241], 0, s[96:97]
	global_load_dword v215, v[240:241], off nt
	v_lshl_add_u64 v[240:241], v[240:241], 0, s[96:97]
	s_mov_b32 s3, 0x18000
	s_mov_b32 s26, 0x48000
	s_mov_b32 s27, 0x54000
	s_mov_b32 s28, 0x60000
	s_mov_b32 s29, 0x6c000
	s_mov_b32 s30, 0x78000
	s_mov_b32 s31, 0x84000
	s_mov_b32 s40, 0x90000
	s_mov_b32 s41, 0x9c000
	s_mov_b32 s72, 0xa8000
	s_mov_b32 s73, 0xb4000
	v_mov_b32_e32 v38, v35
	v_mov_b32_e32 v39, v35
	v_mov_b32_e32 v40, v35
	v_mov_b32_e32 v41, v35
	v_mov_b32_e32 v42, v35
	v_mov_b32_e32 v43, v35
	v_mov_b32_e32 v44, v35
	v_mov_b32_e32 v45, v35
	s_waitcnt vmcnt(57)
	v_mul_f32_e32 v22, 0xbfb8aa3b, v8
	s_waitcnt vmcnt(56)
	v_mul_f32_e32 v23, 0xbfb8aa3b, v9
	v_exp_f32_e32 v23, v23
	v_exp_f32_e32 v22, v22
	s_waitcnt vmcnt(55)
	v_mul_f32_e32 v24, 0xbfb8aa3b, v10
	s_waitcnt vmcnt(54)
	v_mul_f32_e32 v25, 0xbfb8aa3b, v11
	v_exp_f32_e32 v24, v24
	v_exp_f32_e32 v25, v25
	v_add_f32_e32 v23, 1.0, v23
	v_rcp_f32_e32 v23, v23
	s_waitcnt vmcnt(53)
	v_mul_f32_e32 v26, 0xbfb8aa3b, v12
	s_waitcnt vmcnt(52)
	v_mul_f32_e32 v27, 0xbfb8aa3b, v13
	v_exp_f32_e32 v27, v27
	v_add_f32_e32 v22, 1.0, v22
	v_exp_f32_e32 v26, v26
	v_rcp_f32_e32 v22, v22
	v_add_f32_e32 v24, 1.0, v24
	s_waitcnt vmcnt(51)
	v_mul_f32_e32 v28, 0xbfb8aa3b, v14
	v_add_f32_e32 v25, 1.0, v25
	v_rcp_f32_e32 v24, v24
	v_add_f32_e32 v27, 1.0, v27
	v_exp_f32_e32 v28, v28
	v_rcp_f32_e32 v25, v25
	v_mul_f32_e32 v9, v9, v23
	v_rcp_f32_e32 v23, v27
	v_add_f32_e32 v26, 1.0, v26
	v_mul_f32_e32 v8, v8, v22
	v_rcp_f32_e32 v22, v26
	v_mul_f32_e32 v10, v10, v24
	v_add_f32_e32 v26, 1.0, v28
	ds_write_b32 v3, v9 offset:16384
	v_mul_f32_e32 v11, v11, v25
	ds_write2_b32 v3, v8, v10 offset1:1
	v_mul_f32_e32 v10, v13, v23
	s_waitcnt vmcnt(50)
	v_mul_f32_e32 v29, 0xbfb8aa3b, v15
	v_rcp_f32_e32 v9, v26
	ds_write2_b32 v21, v11, v10 offset0:1 offset1:2
	s_waitcnt vmcnt(48)
	v_mul_f32_e32 v10, 0xbfb8aa3b, v17
	v_mul_f32_e32 v8, v12, v22
	v_exp_f32_e32 v12, v29
	v_exp_f32_e32 v10, v10
	v_mul_f32_e32 v9, v14, v9
	ds_write2_b32 v3, v8, v9 offset0:2 offset1:3
	v_add_f32_e32 v8, 1.0, v12
	v_add_f32_e32 v10, 1.0, v10
	v_rcp_f32_e32 v8, v8
	v_rcp_f32_e32 v10, v10
	s_waitcnt vmcnt(47)
	v_mul_f32_e32 v11, 0xbfb8aa3b, v18
	v_exp_f32_e32 v11, v11
	v_mul_f32_e32 v9, 0xbfb8aa3b, v16
	v_mul_f32_e32 v8, v15, v8
	v_mul_f32_e32 v10, v17, v10
	v_exp_f32_e32 v9, v9
	ds_write2_b32 v21, v8, v10 offset0:3 offset1:4
	v_add_f32_e32 v8, 1.0, v11
	s_waitcnt vmcnt(46)
	v_mul_f32_e32 v10, 0xbfb8aa3b, v19
	s_waitcnt vmcnt(45)
	v_mul_f32_e32 v11, 0xbfb8aa3b, v20
	v_exp_f32_e32 v10, v10
	v_exp_f32_e32 v11, v11
	v_add_f32_e32 v9, 1.0, v9
	v_rcp_f32_e32 v9, v9
	v_rcp_f32_e32 v8, v8
	v_add_f32_e32 v10, 1.0, v10
	v_add_f32_e32 v11, 1.0, v11
	s_waitcnt vmcnt(44)
	v_mul_f32_e32 v12, 0xbfb8aa3b, v6
	v_rcp_f32_e32 v10, v10
	v_rcp_f32_e32 v11, v11
	v_exp_f32_e32 v12, v12
	v_mul_f32_e32 v9, v16, v9
	v_mul_f32_e32 v8, v18, v8
	ds_write2_b32 v3, v9, v8 offset0:4 offset1:5
	v_mul_f32_e32 v8, v19, v10
	v_mul_f32_e32 v9, v20, v11
	v_add_f32_e32 v10, 1.0, v12
	s_waitcnt vmcnt(43)
	v_mul_f32_e32 v11, 0xbfb8aa3b, v7
	s_waitcnt vmcnt(42)
	v_mul_f32_e32 v12, 0xbfb8aa3b, v2
	v_rcp_f32_e32 v10, v10
	v_exp_f32_e32 v11, v11
	v_exp_f32_e32 v12, v12
	v_mul_f32_e32 v6, v6, v10
	v_add_f32_e32 v10, 1.0, v11
	v_add_f32_e32 v11, 1.0, v12
	v_rcp_f32_e32 v10, v10
	v_rcp_f32_e32 v11, v11
	ds_write2_b32 v21, v8, v6 offset0:5 offset1:6
	v_mul_f32_e32 v6, v7, v10
	v_mul_f32_e32 v2, v2, v11
	ds_write2_b32 v3, v9, v6 offset0:6 offset1:7
	ds_write_b32 v3, v2 offset:16412
	v_lshrrev_b32_e32 v2, 5, v1
	v_lshl_or_b32 v6, s99, 7, v2
	v_mad_u64_u32 v[2:3], s[24:25], v6, s1, v[4:5]
	v_lshl_add_u64 v[2:3], s[6:7], 2, v[2:3]
	v_lshl_add_u64 v[36:37], v[2:3], 0, v[34:35]
	v_lshl_add_u32 v49, v6, 5, 0
	s_mov_b32 s1, 0xc000
	s_mov_b32 s7, 0x24000
	s_mov_b32 s24, 0x30000
	s_mov_b32 s25, 0x3c000
	s_waitcnt lgkmcnt(0)
	s_barrier
	global_load_dword v216, v[240:241], off nt
	v_lshl_add_u64 v[240:241], v[240:241], 0, s[96:97]
	global_load_dword v217, v[240:241], off nt
	v_lshl_add_u64 v[240:241], v[240:241], 0, s[96:97]
	global_load_dword v218, v[240:241], off nt
	v_lshl_add_u64 v[240:241], v[240:241], 0, s[96:97]
	global_load_dword v219, v[240:241], off nt
	v_lshl_add_u64 v[240:241], v[240:241], 0, s[96:97]
	global_load_dword v220, v[240:241], off nt
	v_lshl_add_u64 v[240:241], v[240:241], 0, s[96:97]
	global_load_dword v221, v[240:241], off nt
	v_lshl_add_u64 v[240:241], v[240:241], 0, s[96:97]
	global_load_dword v222, v[240:241], off nt
	v_lshl_add_u64 v[240:241], v[240:241], 0, s[96:97]
	global_load_dword v223, v[240:241], off nt
	v_lshl_add_u64 v[240:241], v[240:241], 0, s[96:97]
	global_load_dword v224, v[240:241], off nt
	v_lshl_add_u64 v[240:241], v[240:241], 0, s[96:97]
	global_load_dword v225, v[240:241], off nt
	v_lshl_add_u64 v[240:241], v[240:241], 0, s[96:97]
	global_load_dword v226, v[240:241], off nt
	v_lshl_add_u64 v[240:241], v[240:241], 0, s[96:97]
	global_load_dword v227, v[240:241], off nt
	v_lshl_add_u64 v[240:241], v[240:241], 0, s[96:97]
	global_load_dword v228, v[240:241], off nt
	v_lshl_add_u64 v[240:241], v[240:241], 0, s[96:97]
	global_load_dword v229, v[240:241], off nt
	v_lshl_add_u64 v[240:241], v[240:241], 0, s[96:97]
	global_load_dword v230, v[240:241], off nt
	v_lshl_add_u64 v[240:241], v[240:241], 0, s[96:97]
	global_load_dword v231, v[240:241], off nt
	v_lshl_add_u64 v[240:241], v[240:241], 0, s[96:97]
	global_load_dword v232, v[240:241], off nt
	v_lshl_add_u64 v[240:241], v[240:241], 0, s[96:97]
	global_load_dword v233, v[240:241], off nt
	v_lshl_add_u64 v[240:241], v[240:241], 0, s[96:97]
	global_load_dword v234, v[240:241], off nt
	v_lshl_add_u64 v[240:241], v[240:241], 0, s[96:97]
	global_load_dword v235, v[240:241], off nt
	v_lshl_add_u64 v[240:241], v[240:241], 0, s[96:97]
	global_load_dword v236, v[240:241], off nt
	v_lshl_add_u64 v[240:241], v[240:241], 0, s[96:97]
	global_load_dword v237, v[240:241], off nt
	v_lshl_add_u64 v[240:241], v[240:241], 0, s[96:97]
	global_load_dword v238, v[240:241], off nt
	v_lshl_add_u64 v[240:241], v[240:241], 0, s[96:97]
	global_load_dword v239, v[240:241], off nt
	ds_read_b128 v[6:9], v49 offset:0
	ds_read_b128 v[2:5], v49 offset:16
	ds_read_b128 v[14:17], v49 offset:64
	ds_read_b128 v[10:13], v49 offset:80
	ds_read_b128 v[22:25], v49 offset:128
	ds_read_b128 v[18:21], v49 offset:144
	ds_read_b128 v[26:29], v49 offset:192
	ds_read_b128 v[30:33], v49 offset:208
	ds_read_b128 v[50:53], v49 offset:256
	ds_read_b128 v[54:57], v49 offset:272
	ds_read_b128 v[58:61], v49 offset:320
	ds_read_b128 v[62:65], v49 offset:336
	ds_read_b128 v[66:69], v49 offset:384
	ds_read_b128 v[70:73], v49 offset:400
	ds_read_b128 v[74:77], v49 offset:448
	ds_read_b128 v[78:81], v49 offset:464
	ds_read_b128 v[82:85], v49 offset:512
	ds_read_b128 v[86:89], v49 offset:528
	ds_read_b128 v[90:93], v49 offset:576
	ds_read_b128 v[94:97], v49 offset:592
	ds_read_b128 v[98:101], v49 offset:640
	ds_read_b128 v[102:105], v49 offset:656
	ds_read_b128 v[106:109], v49 offset:704
	ds_read_b128 v[110:113], v49 offset:720
	ds_read_b128 v[114:117], v49 offset:768
	ds_read_b128 v[118:121], v49 offset:784
	ds_read_b128 v[122:125], v49 offset:832
	ds_read_b128 v[126:129], v49 offset:848
	ds_read_b128 v[130:133], v49 offset:896
	ds_read_b128 v[134:137], v49 offset:912
	ds_read_b128 v[138:141], v49 offset:960
	ds_read_b128 v[142:145], v49 offset:976
	v_add_u32_e32 v49, 0x400, v49
	s_waitcnt lgkmcnt(0)
	s_waitcnt vmcnt(63)
	v_pk_fma_f32 v[38:39], v[176:177], v[6:7], v[38:39] op_sel_hi:[0,1,1]
	v_pk_fma_f32 v[40:41], v[176:177], v[8:9], v[40:41] op_sel_hi:[0,1,1]
	v_pk_fma_f32 v[42:43], v[176:177], v[2:3], v[42:43] op_sel_hi:[0,1,1]
	v_pk_fma_f32 v[44:45], v[176:177], v[4:5], v[44:45] op_sel_hi:[0,1,1]
	s_waitcnt vmcnt(62)
	v_pk_fma_f32 v[38:39], v[176:177], v[14:15], v[38:39] op_sel:[1,0,0] op_sel_hi:[1,1,1]
	v_pk_fma_f32 v[40:41], v[176:177], v[16:17], v[40:41] op_sel:[1,0,0] op_sel_hi:[1,1,1]
	v_pk_fma_f32 v[42:43], v[176:177], v[10:11], v[42:43] op_sel:[1,0,0] op_sel_hi:[1,1,1]
	v_pk_fma_f32 v[44:45], v[176:177], v[12:13], v[44:45] op_sel:[1,0,0] op_sel_hi:[1,1,1]
	s_waitcnt vmcnt(61)
	v_pk_fma_f32 v[38:39], v[178:179], v[22:23], v[38:39] op_sel_hi:[0,1,1]
	v_pk_fma_f32 v[40:41], v[178:179], v[24:25], v[40:41] op_sel_hi:[0,1,1]
	v_pk_fma_f32 v[42:43], v[178:179], v[18:19], v[42:43] op_sel_hi:[0,1,1]
	v_pk_fma_f32 v[44:45], v[178:179], v[20:21], v[44:45] op_sel_hi:[0,1,1]
	s_waitcnt vmcnt(60)
	v_pk_fma_f32 v[38:39], v[178:179], v[26:27], v[38:39] op_sel:[1,0,0] op_sel_hi:[1,1,1]
	v_pk_fma_f32 v[40:41], v[178:179], v[28:29], v[40:41] op_sel:[1,0,0] op_sel_hi:[1,1,1]
	v_pk_fma_f32 v[42:43], v[178:179], v[30:31], v[42:43] op_sel:[1,0,0] op_sel_hi:[1,1,1]
	v_pk_fma_f32 v[44:45], v[178:179], v[32:33], v[44:45] op_sel:[1,0,0] op_sel_hi:[1,1,1]
	s_waitcnt vmcnt(59)
	v_pk_fma_f32 v[38:39], v[180:181], v[50:51], v[38:39] op_sel_hi:[0,1,1]
	v_pk_fma_f32 v[40:41], v[180:181], v[52:53], v[40:41] op_sel_hi:[0,1,1]
	v_pk_fma_f32 v[42:43], v[180:181], v[54:55], v[42:43] op_sel_hi:[0,1,1]
	v_pk_fma_f32 v[44:45], v[180:181], v[56:57], v[44:45] op_sel_hi:[0,1,1]
	s_waitcnt vmcnt(58)
	v_pk_fma_f32 v[38:39], v[180:181], v[58:59], v[38:39] op_sel:[1,0,0] op_sel_hi:[1,1,1]
	v_pk_fma_f32 v[40:41], v[180:181], v[60:61], v[40:41] op_sel:[1,0,0] op_sel_hi:[1,1,1]
	v_pk_fma_f32 v[42:43], v[180:181], v[62:63], v[42:43] op_sel:[1,0,0] op_sel_hi:[1,1,1]
	v_pk_fma_f32 v[44:45], v[180:181], v[64:65], v[44:45] op_sel:[1,0,0] op_sel_hi:[1,1,1]
	s_waitcnt vmcnt(57)
	v_pk_fma_f32 v[38:39], v[182:183], v[66:67], v[38:39] op_sel_hi:[0,1,1]
	v_pk_fma_f32 v[40:41], v[182:183], v[68:69], v[40:41] op_sel_hi:[0,1,1]
	v_pk_fma_f32 v[42:43], v[182:183], v[70:71], v[42:43] op_sel_hi:[0,1,1]
	v_pk_fma_f32 v[44:45], v[182:183], v[72:73], v[44:45] op_sel_hi:[0,1,1]
	s_waitcnt vmcnt(56)
	v_pk_fma_f32 v[38:39], v[182:183], v[74:75], v[38:39] op_sel:[1,0,0] op_sel_hi:[1,1,1]
	v_pk_fma_f32 v[40:41], v[182:183], v[76:77], v[40:41] op_sel:[1,0,0] op_sel_hi:[1,1,1]
	v_pk_fma_f32 v[42:43], v[182:183], v[78:79], v[42:43] op_sel:[1,0,0] op_sel_hi:[1,1,1]
	v_pk_fma_f32 v[44:45], v[182:183], v[80:81], v[44:45] op_sel:[1,0,0] op_sel_hi:[1,1,1]
	s_waitcnt vmcnt(55)
	v_pk_fma_f32 v[38:39], v[184:185], v[82:83], v[38:39] op_sel_hi:[0,1,1]
	v_pk_fma_f32 v[40:41], v[184:185], v[84:85], v[40:41] op_sel_hi:[0,1,1]
	v_pk_fma_f32 v[42:43], v[184:185], v[86:87], v[42:43] op_sel_hi:[0,1,1]
	v_pk_fma_f32 v[44:45], v[184:185], v[88:89], v[44:45] op_sel_hi:[0,1,1]
	s_waitcnt vmcnt(54)
	v_pk_fma_f32 v[38:39], v[184:185], v[90:91], v[38:39] op_sel:[1,0,0] op_sel_hi:[1,1,1]
	v_pk_fma_f32 v[40:41], v[184:185], v[92:93], v[40:41] op_sel:[1,0,0] op_sel_hi:[1,1,1]
	v_pk_fma_f32 v[42:43], v[184:185], v[94:95], v[42:43] op_sel:[1,0,0] op_sel_hi:[1,1,1]
	v_pk_fma_f32 v[44:45], v[184:185], v[96:97], v[44:45] op_sel:[1,0,0] op_sel_hi:[1,1,1]
	s_waitcnt vmcnt(53)
	v_pk_fma_f32 v[38:39], v[186:187], v[98:99], v[38:39] op_sel_hi:[0,1,1]
	v_pk_fma_f32 v[40:41], v[186:187], v[100:101], v[40:41] op_sel_hi:[0,1,1]
	v_pk_fma_f32 v[42:43], v[186:187], v[102:103], v[42:43] op_sel_hi:[0,1,1]
	v_pk_fma_f32 v[44:45], v[186:187], v[104:105], v[44:45] op_sel_hi:[0,1,1]
	s_waitcnt vmcnt(52)
	v_pk_fma_f32 v[38:39], v[186:187], v[106:107], v[38:39] op_sel:[1,0,0] op_sel_hi:[1,1,1]
	v_pk_fma_f32 v[40:41], v[186:187], v[108:109], v[40:41] op_sel:[1,0,0] op_sel_hi:[1,1,1]
	v_pk_fma_f32 v[42:43], v[186:187], v[110:111], v[42:43] op_sel:[1,0,0] op_sel_hi:[1,1,1]
	v_pk_fma_f32 v[44:45], v[186:187], v[112:113], v[44:45] op_sel:[1,0,0] op_sel_hi:[1,1,1]
	s_waitcnt vmcnt(51)
	v_pk_fma_f32 v[38:39], v[188:189], v[114:115], v[38:39] op_sel_hi:[0,1,1]
	v_pk_fma_f32 v[40:41], v[188:189], v[116:117], v[40:41] op_sel_hi:[0,1,1]
	v_pk_fma_f32 v[42:43], v[188:189], v[118:119], v[42:43] op_sel_hi:[0,1,1]
	v_pk_fma_f32 v[44:45], v[188:189], v[120:121], v[44:45] op_sel_hi:[0,1,1]
	s_waitcnt vmcnt(50)
	v_pk_fma_f32 v[38:39], v[188:189], v[122:123], v[38:39] op_sel:[1,0,0] op_sel_hi:[1,1,1]
	v_pk_fma_f32 v[40:41], v[188:189], v[124:125], v[40:41] op_sel:[1,0,0] op_sel_hi:[1,1,1]
	v_pk_fma_f32 v[42:43], v[188:189], v[126:127], v[42:43] op_sel:[1,0,0] op_sel_hi:[1,1,1]
	v_pk_fma_f32 v[44:45], v[188:189], v[128:129], v[44:45] op_sel:[1,0,0] op_sel_hi:[1,1,1]
	s_waitcnt vmcnt(49)
	v_pk_fma_f32 v[38:39], v[190:191], v[130:131], v[38:39] op_sel_hi:[0,1,1]
	v_pk_fma_f32 v[40:41], v[190:191], v[132:133], v[40:41] op_sel_hi:[0,1,1]
	v_pk_fma_f32 v[42:43], v[190:191], v[134:135], v[42:43] op_sel_hi:[0,1,1]
	v_pk_fma_f32 v[44:45], v[190:191], v[136:137], v[44:45] op_sel_hi:[0,1,1]
	s_waitcnt vmcnt(48)
	v_pk_fma_f32 v[38:39], v[190:191], v[138:139], v[38:39] op_sel:[1,0,0] op_sel_hi:[1,1,1]
	v_pk_fma_f32 v[40:41], v[190:191], v[140:141], v[40:41] op_sel:[1,0,0] op_sel_hi:[1,1,1]
	v_pk_fma_f32 v[42:43], v[190:191], v[142:143], v[42:43] op_sel:[1,0,0] op_sel_hi:[1,1,1]
	v_pk_fma_f32 v[44:45], v[190:191], v[144:145], v[44:45] op_sel:[1,0,0] op_sel_hi:[1,1,1]
	ds_read_b128 v[6:9], v49 offset:0
	ds_read_b128 v[2:5], v49 offset:16
	ds_read_b128 v[14:17], v49 offset:64
	ds_read_b128 v[10:13], v49 offset:80
	ds_read_b128 v[22:25], v49 offset:128
	ds_read_b128 v[18:21], v49 offset:144
	ds_read_b128 v[26:29], v49 offset:192
	ds_read_b128 v[30:33], v49 offset:208
	ds_read_b128 v[50:53], v49 offset:256
	ds_read_b128 v[54:57], v49 offset:272
	ds_read_b128 v[58:61], v49 offset:320
	ds_read_b128 v[62:65], v49 offset:336
	ds_read_b128 v[66:69], v49 offset:384
	ds_read_b128 v[70:73], v49 offset:400
	ds_read_b128 v[74:77], v49 offset:448
	ds_read_b128 v[78:81], v49 offset:464
	ds_read_b128 v[82:85], v49 offset:512
	ds_read_b128 v[86:89], v49 offset:528
	ds_read_b128 v[90:93], v49 offset:576
	ds_read_b128 v[94:97], v49 offset:592
	ds_read_b128 v[98:101], v49 offset:640
	ds_read_b128 v[102:105], v49 offset:656
	ds_read_b128 v[106:109], v49 offset:704
	ds_read_b128 v[110:113], v49 offset:720
	ds_read_b128 v[114:117], v49 offset:768
	ds_read_b128 v[118:121], v49 offset:784
	ds_read_b128 v[122:125], v49 offset:832
	ds_read_b128 v[126:129], v49 offset:848
	ds_read_b128 v[130:133], v49 offset:896
	ds_read_b128 v[134:137], v49 offset:912
	ds_read_b128 v[138:141], v49 offset:960
	ds_read_b128 v[142:145], v49 offset:976
	v_add_u32_e32 v49, 0x400, v49
	s_waitcnt lgkmcnt(0)
	s_waitcnt vmcnt(47)
	v_pk_fma_f32 v[38:39], v[192:193], v[6:7], v[38:39] op_sel_hi:[0,1,1]
	v_pk_fma_f32 v[40:41], v[192:193], v[8:9], v[40:41] op_sel_hi:[0,1,1]
	v_pk_fma_f32 v[42:43], v[192:193], v[2:3], v[42:43] op_sel_hi:[0,1,1]
	v_pk_fma_f32 v[44:45], v[192:193], v[4:5], v[44:45] op_sel_hi:[0,1,1]
	s_waitcnt vmcnt(46)
	v_pk_fma_f32 v[38:39], v[192:193], v[14:15], v[38:39] op_sel:[1,0,0] op_sel_hi:[1,1,1]
	v_pk_fma_f32 v[40:41], v[192:193], v[16:17], v[40:41] op_sel:[1,0,0] op_sel_hi:[1,1,1]
	v_pk_fma_f32 v[42:43], v[192:193], v[10:11], v[42:43] op_sel:[1,0,0] op_sel_hi:[1,1,1]
	v_pk_fma_f32 v[44:45], v[192:193], v[12:13], v[44:45] op_sel:[1,0,0] op_sel_hi:[1,1,1]
	s_waitcnt vmcnt(45)
	v_pk_fma_f32 v[38:39], v[194:195], v[22:23], v[38:39] op_sel_hi:[0,1,1]
	v_pk_fma_f32 v[40:41], v[194:195], v[24:25], v[40:41] op_sel_hi:[0,1,1]
	v_pk_fma_f32 v[42:43], v[194:195], v[18:19], v[42:43] op_sel_hi:[0,1,1]
	v_pk_fma_f32 v[44:45], v[194:195], v[20:21], v[44:45] op_sel_hi:[0,1,1]
	s_waitcnt vmcnt(44)
	v_pk_fma_f32 v[38:39], v[194:195], v[26:27], v[38:39] op_sel:[1,0,0] op_sel_hi:[1,1,1]
	v_pk_fma_f32 v[40:41], v[194:195], v[28:29], v[40:41] op_sel:[1,0,0] op_sel_hi:[1,1,1]
	v_pk_fma_f32 v[42:43], v[194:195], v[30:31], v[42:43] op_sel:[1,0,0] op_sel_hi:[1,1,1]
	v_pk_fma_f32 v[44:45], v[194:195], v[32:33], v[44:45] op_sel:[1,0,0] op_sel_hi:[1,1,1]
	s_waitcnt vmcnt(43)
	v_pk_fma_f32 v[38:39], v[196:197], v[50:51], v[38:39] op_sel_hi:[0,1,1]
	v_pk_fma_f32 v[40:41], v[196:197], v[52:53], v[40:41] op_sel_hi:[0,1,1]
	v_pk_fma_f32 v[42:43], v[196:197], v[54:55], v[42:43] op_sel_hi:[0,1,1]
	v_pk_fma_f32 v[44:45], v[196:197], v[56:57], v[44:45] op_sel_hi:[0,1,1]
	s_waitcnt vmcnt(42)
	v_pk_fma_f32 v[38:39], v[196:197], v[58:59], v[38:39] op_sel:[1,0,0] op_sel_hi:[1,1,1]
	v_pk_fma_f32 v[40:41], v[196:197], v[60:61], v[40:41] op_sel:[1,0,0] op_sel_hi:[1,1,1]
	v_pk_fma_f32 v[42:43], v[196:197], v[62:63], v[42:43] op_sel:[1,0,0] op_sel_hi:[1,1,1]
	v_pk_fma_f32 v[44:45], v[196:197], v[64:65], v[44:45] op_sel:[1,0,0] op_sel_hi:[1,1,1]
	s_waitcnt vmcnt(41)
	v_pk_fma_f32 v[38:39], v[198:199], v[66:67], v[38:39] op_sel_hi:[0,1,1]
	v_pk_fma_f32 v[40:41], v[198:199], v[68:69], v[40:41] op_sel_hi:[0,1,1]
	v_pk_fma_f32 v[42:43], v[198:199], v[70:71], v[42:43] op_sel_hi:[0,1,1]
	v_pk_fma_f32 v[44:45], v[198:199], v[72:73], v[44:45] op_sel_hi:[0,1,1]
	s_waitcnt vmcnt(40)
	v_pk_fma_f32 v[38:39], v[198:199], v[74:75], v[38:39] op_sel:[1,0,0] op_sel_hi:[1,1,1]
	v_pk_fma_f32 v[40:41], v[198:199], v[76:77], v[40:41] op_sel:[1,0,0] op_sel_hi:[1,1,1]
	v_pk_fma_f32 v[42:43], v[198:199], v[78:79], v[42:43] op_sel:[1,0,0] op_sel_hi:[1,1,1]
	v_pk_fma_f32 v[44:45], v[198:199], v[80:81], v[44:45] op_sel:[1,0,0] op_sel_hi:[1,1,1]
	s_waitcnt vmcnt(39)
	v_pk_fma_f32 v[38:39], v[200:201], v[82:83], v[38:39] op_sel_hi:[0,1,1]
	v_pk_fma_f32 v[40:41], v[200:201], v[84:85], v[40:41] op_sel_hi:[0,1,1]
	v_pk_fma_f32 v[42:43], v[200:201], v[86:87], v[42:43] op_sel_hi:[0,1,1]
	v_pk_fma_f32 v[44:45], v[200:201], v[88:89], v[44:45] op_sel_hi:[0,1,1]
	s_waitcnt vmcnt(38)
	v_pk_fma_f32 v[38:39], v[200:201], v[90:91], v[38:39] op_sel:[1,0,0] op_sel_hi:[1,1,1]
	v_pk_fma_f32 v[40:41], v[200:201], v[92:93], v[40:41] op_sel:[1,0,0] op_sel_hi:[1,1,1]
	v_pk_fma_f32 v[42:43], v[200:201], v[94:95], v[42:43] op_sel:[1,0,0] op_sel_hi:[1,1,1]
	v_pk_fma_f32 v[44:45], v[200:201], v[96:97], v[44:45] op_sel:[1,0,0] op_sel_hi:[1,1,1]
	s_waitcnt vmcnt(37)
	v_pk_fma_f32 v[38:39], v[202:203], v[98:99], v[38:39] op_sel_hi:[0,1,1]
	v_pk_fma_f32 v[40:41], v[202:203], v[100:101], v[40:41] op_sel_hi:[0,1,1]
	v_pk_fma_f32 v[42:43], v[202:203], v[102:103], v[42:43] op_sel_hi:[0,1,1]
	v_pk_fma_f32 v[44:45], v[202:203], v[104:105], v[44:45] op_sel_hi:[0,1,1]
	s_waitcnt vmcnt(36)
	v_pk_fma_f32 v[38:39], v[202:203], v[106:107], v[38:39] op_sel:[1,0,0] op_sel_hi:[1,1,1]
	v_pk_fma_f32 v[40:41], v[202:203], v[108:109], v[40:41] op_sel:[1,0,0] op_sel_hi:[1,1,1]
	v_pk_fma_f32 v[42:43], v[202:203], v[110:111], v[42:43] op_sel:[1,0,0] op_sel_hi:[1,1,1]
	v_pk_fma_f32 v[44:45], v[202:203], v[112:113], v[44:45] op_sel:[1,0,0] op_sel_hi:[1,1,1]
	s_waitcnt vmcnt(35)
	v_pk_fma_f32 v[38:39], v[204:205], v[114:115], v[38:39] op_sel_hi:[0,1,1]
	v_pk_fma_f32 v[40:41], v[204:205], v[116:117], v[40:41] op_sel_hi:[0,1,1]
	v_pk_fma_f32 v[42:43], v[204:205], v[118:119], v[42:43] op_sel_hi:[0,1,1]
	v_pk_fma_f32 v[44:45], v[204:205], v[120:121], v[44:45] op_sel_hi:[0,1,1]
	s_waitcnt vmcnt(34)
	v_pk_fma_f32 v[38:39], v[204:205], v[122:123], v[38:39] op_sel:[1,0,0] op_sel_hi:[1,1,1]
	v_pk_fma_f32 v[40:41], v[204:205], v[124:125], v[40:41] op_sel:[1,0,0] op_sel_hi:[1,1,1]
	v_pk_fma_f32 v[42:43], v[204:205], v[126:127], v[42:43] op_sel:[1,0,0] op_sel_hi:[1,1,1]
	v_pk_fma_f32 v[44:45], v[204:205], v[128:129], v[44:45] op_sel:[1,0,0] op_sel_hi:[1,1,1]
	s_waitcnt vmcnt(33)
	v_pk_fma_f32 v[38:39], v[206:207], v[130:131], v[38:39] op_sel_hi:[0,1,1]
	v_pk_fma_f32 v[40:41], v[206:207], v[132:133], v[40:41] op_sel_hi:[0,1,1]
	v_pk_fma_f32 v[42:43], v[206:207], v[134:135], v[42:43] op_sel_hi:[0,1,1]
	v_pk_fma_f32 v[44:45], v[206:207], v[136:137], v[44:45] op_sel_hi:[0,1,1]
	s_waitcnt vmcnt(32)
	v_pk_fma_f32 v[38:39], v[206:207], v[138:139], v[38:39] op_sel:[1,0,0] op_sel_hi:[1,1,1]
	v_pk_fma_f32 v[40:41], v[206:207], v[140:141], v[40:41] op_sel:[1,0,0] op_sel_hi:[1,1,1]
	v_pk_fma_f32 v[42:43], v[206:207], v[142:143], v[42:43] op_sel:[1,0,0] op_sel_hi:[1,1,1]
	v_pk_fma_f32 v[44:45], v[206:207], v[144:145], v[44:45] op_sel:[1,0,0] op_sel_hi:[1,1,1]
	ds_read_b128 v[6:9], v49 offset:0
	ds_read_b128 v[2:5], v49 offset:16
	ds_read_b128 v[14:17], v49 offset:64
	ds_read_b128 v[10:13], v49 offset:80
	ds_read_b128 v[22:25], v49 offset:128
	ds_read_b128 v[18:21], v49 offset:144
	ds_read_b128 v[26:29], v49 offset:192
	ds_read_b128 v[30:33], v49 offset:208
	ds_read_b128 v[50:53], v49 offset:256
	ds_read_b128 v[54:57], v49 offset:272
	ds_read_b128 v[58:61], v49 offset:320
	ds_read_b128 v[62:65], v49 offset:336
	ds_read_b128 v[66:69], v49 offset:384
	ds_read_b128 v[70:73], v49 offset:400
	ds_read_b128 v[74:77], v49 offset:448
	ds_read_b128 v[78:81], v49 offset:464
	ds_read_b128 v[82:85], v49 offset:512
	ds_read_b128 v[86:89], v49 offset:528
	ds_read_b128 v[90:93], v49 offset:576
	ds_read_b128 v[94:97], v49 offset:592
	ds_read_b128 v[98:101], v49 offset:640
	ds_read_b128 v[102:105], v49 offset:656
	ds_read_b128 v[106:109], v49 offset:704
	ds_read_b128 v[110:113], v49 offset:720
	ds_read_b128 v[114:117], v49 offset:768
	ds_read_b128 v[118:121], v49 offset:784
	ds_read_b128 v[122:125], v49 offset:832
	ds_read_b128 v[126:129], v49 offset:848
	ds_read_b128 v[130:133], v49 offset:896
	ds_read_b128 v[134:137], v49 offset:912
	ds_read_b128 v[138:141], v49 offset:960
	ds_read_b128 v[142:145], v49 offset:976
	v_add_u32_e32 v49, 0x400, v49
	s_waitcnt lgkmcnt(0)
	s_waitcnt vmcnt(31)
	v_pk_fma_f32 v[38:39], v[208:209], v[6:7], v[38:39] op_sel_hi:[0,1,1]
	v_pk_fma_f32 v[40:41], v[208:209], v[8:9], v[40:41] op_sel_hi:[0,1,1]
	v_pk_fma_f32 v[42:43], v[208:209], v[2:3], v[42:43] op_sel_hi:[0,1,1]
	v_pk_fma_f32 v[44:45], v[208:209], v[4:5], v[44:45] op_sel_hi:[0,1,1]
	s_waitcnt vmcnt(30)
	v_pk_fma_f32 v[38:39], v[208:209], v[14:15], v[38:39] op_sel:[1,0,0] op_sel_hi:[1,1,1]
	v_pk_fma_f32 v[40:41], v[208:209], v[16:17], v[40:41] op_sel:[1,0,0] op_sel_hi:[1,1,1]
	v_pk_fma_f32 v[42:43], v[208:209], v[10:11], v[42:43] op_sel:[1,0,0] op_sel_hi:[1,1,1]
	v_pk_fma_f32 v[44:45], v[208:209], v[12:13], v[44:45] op_sel:[1,0,0] op_sel_hi:[1,1,1]
	s_waitcnt vmcnt(29)
	v_pk_fma_f32 v[38:39], v[210:211], v[22:23], v[38:39] op_sel_hi:[0,1,1]
	v_pk_fma_f32 v[40:41], v[210:211], v[24:25], v[40:41] op_sel_hi:[0,1,1]
	v_pk_fma_f32 v[42:43], v[210:211], v[18:19], v[42:43] op_sel_hi:[0,1,1]
	v_pk_fma_f32 v[44:45], v[210:211], v[20:21], v[44:45] op_sel_hi:[0,1,1]
	s_waitcnt vmcnt(28)
	v_pk_fma_f32 v[38:39], v[210:211], v[26:27], v[38:39] op_sel:[1,0,0] op_sel_hi:[1,1,1]
	v_pk_fma_f32 v[40:41], v[210:211], v[28:29], v[40:41] op_sel:[1,0,0] op_sel_hi:[1,1,1]
	v_pk_fma_f32 v[42:43], v[210:211], v[30:31], v[42:43] op_sel:[1,0,0] op_sel_hi:[1,1,1]
	v_pk_fma_f32 v[44:45], v[210:211], v[32:33], v[44:45] op_sel:[1,0,0] op_sel_hi:[1,1,1]
	s_waitcnt vmcnt(27)
	v_pk_fma_f32 v[38:39], v[212:213], v[50:51], v[38:39] op_sel_hi:[0,1,1]
	v_pk_fma_f32 v[40:41], v[212:213], v[52:53], v[40:41] op_sel_hi:[0,1,1]
	v_pk_fma_f32 v[42:43], v[212:213], v[54:55], v[42:43] op_sel_hi:[0,1,1]
	v_pk_fma_f32 v[44:45], v[212:213], v[56:57], v[44:45] op_sel_hi:[0,1,1]
	s_waitcnt vmcnt(26)
	v_pk_fma_f32 v[38:39], v[212:213], v[58:59], v[38:39] op_sel:[1,0,0] op_sel_hi:[1,1,1]
	v_pk_fma_f32 v[40:41], v[212:213], v[60:61], v[40:41] op_sel:[1,0,0] op_sel_hi:[1,1,1]
	v_pk_fma_f32 v[42:43], v[212:213], v[62:63], v[42:43] op_sel:[1,0,0] op_sel_hi:[1,1,1]
	v_pk_fma_f32 v[44:45], v[212:213], v[64:65], v[44:45] op_sel:[1,0,0] op_sel_hi:[1,1,1]
	s_waitcnt vmcnt(25)
	v_pk_fma_f32 v[38:39], v[214:215], v[66:67], v[38:39] op_sel_hi:[0,1,1]
	v_pk_fma_f32 v[40:41], v[214:215], v[68:69], v[40:41] op_sel_hi:[0,1,1]
	v_pk_fma_f32 v[42:43], v[214:215], v[70:71], v[42:43] op_sel_hi:[0,1,1]
	v_pk_fma_f32 v[44:45], v[214:215], v[72:73], v[44:45] op_sel_hi:[0,1,1]
	s_waitcnt vmcnt(24)
	v_pk_fma_f32 v[38:39], v[214:215], v[74:75], v[38:39] op_sel:[1,0,0] op_sel_hi:[1,1,1]
	v_pk_fma_f32 v[40:41], v[214:215], v[76:77], v[40:41] op_sel:[1,0,0] op_sel_hi:[1,1,1]
	v_pk_fma_f32 v[42:43], v[214:215], v[78:79], v[42:43] op_sel:[1,0,0] op_sel_hi:[1,1,1]
	v_pk_fma_f32 v[44:45], v[214:215], v[80:81], v[44:45] op_sel:[1,0,0] op_sel_hi:[1,1,1]
	s_waitcnt vmcnt(23)
	v_pk_fma_f32 v[38:39], v[216:217], v[82:83], v[38:39] op_sel_hi:[0,1,1]
	v_pk_fma_f32 v[40:41], v[216:217], v[84:85], v[40:41] op_sel_hi:[0,1,1]
	v_pk_fma_f32 v[42:43], v[216:217], v[86:87], v[42:43] op_sel_hi:[0,1,1]
	v_pk_fma_f32 v[44:45], v[216:217], v[88:89], v[44:45] op_sel_hi:[0,1,1]
	s_waitcnt vmcnt(22)
	v_pk_fma_f32 v[38:39], v[216:217], v[90:91], v[38:39] op_sel:[1,0,0] op_sel_hi:[1,1,1]
	v_pk_fma_f32 v[40:41], v[216:217], v[92:93], v[40:41] op_sel:[1,0,0] op_sel_hi:[1,1,1]
	v_pk_fma_f32 v[42:43], v[216:217], v[94:95], v[42:43] op_sel:[1,0,0] op_sel_hi:[1,1,1]
	v_pk_fma_f32 v[44:45], v[216:217], v[96:97], v[44:45] op_sel:[1,0,0] op_sel_hi:[1,1,1]
	s_waitcnt vmcnt(21)
	v_pk_fma_f32 v[38:39], v[218:219], v[98:99], v[38:39] op_sel_hi:[0,1,1]
	v_pk_fma_f32 v[40:41], v[218:219], v[100:101], v[40:41] op_sel_hi:[0,1,1]
	v_pk_fma_f32 v[42:43], v[218:219], v[102:103], v[42:43] op_sel_hi:[0,1,1]
	v_pk_fma_f32 v[44:45], v[218:219], v[104:105], v[44:45] op_sel_hi:[0,1,1]
	s_waitcnt vmcnt(20)
	v_pk_fma_f32 v[38:39], v[218:219], v[106:107], v[38:39] op_sel:[1,0,0] op_sel_hi:[1,1,1]
	v_pk_fma_f32 v[40:41], v[218:219], v[108:109], v[40:41] op_sel:[1,0,0] op_sel_hi:[1,1,1]
	v_pk_fma_f32 v[42:43], v[218:219], v[110:111], v[42:43] op_sel:[1,0,0] op_sel_hi:[1,1,1]
	v_pk_fma_f32 v[44:45], v[218:219], v[112:113], v[44:45] op_sel:[1,0,0] op_sel_hi:[1,1,1]
	s_waitcnt vmcnt(19)
	v_pk_fma_f32 v[38:39], v[220:221], v[114:115], v[38:39] op_sel_hi:[0,1,1]
	v_pk_fma_f32 v[40:41], v[220:221], v[116:117], v[40:41] op_sel_hi:[0,1,1]
	v_pk_fma_f32 v[42:43], v[220:221], v[118:119], v[42:43] op_sel_hi:[0,1,1]
	v_pk_fma_f32 v[44:45], v[220:221], v[120:121], v[44:45] op_sel_hi:[0,1,1]
	s_waitcnt vmcnt(18)
	v_pk_fma_f32 v[38:39], v[220:221], v[122:123], v[38:39] op_sel:[1,0,0] op_sel_hi:[1,1,1]
	v_pk_fma_f32 v[40:41], v[220:221], v[124:125], v[40:41] op_sel:[1,0,0] op_sel_hi:[1,1,1]
	v_pk_fma_f32 v[42:43], v[220:221], v[126:127], v[42:43] op_sel:[1,0,0] op_sel_hi:[1,1,1]
	v_pk_fma_f32 v[44:45], v[220:221], v[128:129], v[44:45] op_sel:[1,0,0] op_sel_hi:[1,1,1]
	s_waitcnt vmcnt(17)
	v_pk_fma_f32 v[38:39], v[222:223], v[130:131], v[38:39] op_sel_hi:[0,1,1]
	v_pk_fma_f32 v[40:41], v[222:223], v[132:133], v[40:41] op_sel_hi:[0,1,1]
	v_pk_fma_f32 v[42:43], v[222:223], v[134:135], v[42:43] op_sel_hi:[0,1,1]
	v_pk_fma_f32 v[44:45], v[222:223], v[136:137], v[44:45] op_sel_hi:[0,1,1]
	s_waitcnt vmcnt(16)
	v_pk_fma_f32 v[38:39], v[222:223], v[138:139], v[38:39] op_sel:[1,0,0] op_sel_hi:[1,1,1]
	v_pk_fma_f32 v[40:41], v[222:223], v[140:141], v[40:41] op_sel:[1,0,0] op_sel_hi:[1,1,1]
	v_pk_fma_f32 v[42:43], v[222:223], v[142:143], v[42:43] op_sel:[1,0,0] op_sel_hi:[1,1,1]
	v_pk_fma_f32 v[44:45], v[222:223], v[144:145], v[44:45] op_sel:[1,0,0] op_sel_hi:[1,1,1]
	ds_read_b128 v[6:9], v49 offset:0
	ds_read_b128 v[2:5], v49 offset:16
	ds_read_b128 v[14:17], v49 offset:64
	ds_read_b128 v[10:13], v49 offset:80
	ds_read_b128 v[22:25], v49 offset:128
	ds_read_b128 v[18:21], v49 offset:144
	ds_read_b128 v[26:29], v49 offset:192
	ds_read_b128 v[30:33], v49 offset:208
	ds_read_b128 v[50:53], v49 offset:256
	ds_read_b128 v[54:57], v49 offset:272
	ds_read_b128 v[58:61], v49 offset:320
	ds_read_b128 v[62:65], v49 offset:336
	ds_read_b128 v[66:69], v49 offset:384
	ds_read_b128 v[70:73], v49 offset:400
	ds_read_b128 v[74:77], v49 offset:448
	ds_read_b128 v[78:81], v49 offset:464
	ds_read_b128 v[82:85], v49 offset:512
	ds_read_b128 v[86:89], v49 offset:528
	ds_read_b128 v[90:93], v49 offset:576
	ds_read_b128 v[94:97], v49 offset:592
	ds_read_b128 v[98:101], v49 offset:640
	ds_read_b128 v[102:105], v49 offset:656
	ds_read_b128 v[106:109], v49 offset:704
	ds_read_b128 v[110:113], v49 offset:720
	ds_read_b128 v[114:117], v49 offset:768
	ds_read_b128 v[118:121], v49 offset:784
	ds_read_b128 v[122:125], v49 offset:832
	ds_read_b128 v[126:129], v49 offset:848
	ds_read_b128 v[130:133], v49 offset:896
	ds_read_b128 v[134:137], v49 offset:912
	ds_read_b128 v[138:141], v49 offset:960
	ds_read_b128 v[142:145], v49 offset:976
	v_add_u32_e32 v49, 0x400, v49
	s_waitcnt lgkmcnt(0)
	s_waitcnt vmcnt(15)
	v_pk_fma_f32 v[38:39], v[224:225], v[6:7], v[38:39] op_sel_hi:[0,1,1]
	v_pk_fma_f32 v[40:41], v[224:225], v[8:9], v[40:41] op_sel_hi:[0,1,1]
	v_pk_fma_f32 v[42:43], v[224:225], v[2:3], v[42:43] op_sel_hi:[0,1,1]
	v_pk_fma_f32 v[44:45], v[224:225], v[4:5], v[44:45] op_sel_hi:[0,1,1]
	s_waitcnt vmcnt(14)
	v_pk_fma_f32 v[38:39], v[224:225], v[14:15], v[38:39] op_sel:[1,0,0] op_sel_hi:[1,1,1]
	v_pk_fma_f32 v[40:41], v[224:225], v[16:17], v[40:41] op_sel:[1,0,0] op_sel_hi:[1,1,1]
	v_pk_fma_f32 v[42:43], v[224:225], v[10:11], v[42:43] op_sel:[1,0,0] op_sel_hi:[1,1,1]
	v_pk_fma_f32 v[44:45], v[224:225], v[12:13], v[44:45] op_sel:[1,0,0] op_sel_hi:[1,1,1]
	s_waitcnt vmcnt(13)
	v_pk_fma_f32 v[38:39], v[226:227], v[22:23], v[38:39] op_sel_hi:[0,1,1]
	v_pk_fma_f32 v[40:41], v[226:227], v[24:25], v[40:41] op_sel_hi:[0,1,1]
	v_pk_fma_f32 v[42:43], v[226:227], v[18:19], v[42:43] op_sel_hi:[0,1,1]
	v_pk_fma_f32 v[44:45], v[226:227], v[20:21], v[44:45] op_sel_hi:[0,1,1]
	s_waitcnt vmcnt(12)
	v_pk_fma_f32 v[38:39], v[226:227], v[26:27], v[38:39] op_sel:[1,0,0] op_sel_hi:[1,1,1]
	v_pk_fma_f32 v[40:41], v[226:227], v[28:29], v[40:41] op_sel:[1,0,0] op_sel_hi:[1,1,1]
	v_pk_fma_f32 v[42:43], v[226:227], v[30:31], v[42:43] op_sel:[1,0,0] op_sel_hi:[1,1,1]
	v_pk_fma_f32 v[44:45], v[226:227], v[32:33], v[44:45] op_sel:[1,0,0] op_sel_hi:[1,1,1]
	s_waitcnt vmcnt(11)
	v_pk_fma_f32 v[38:39], v[228:229], v[50:51], v[38:39] op_sel_hi:[0,1,1]
	v_pk_fma_f32 v[40:41], v[228:229], v[52:53], v[40:41] op_sel_hi:[0,1,1]
	v_pk_fma_f32 v[42:43], v[228:229], v[54:55], v[42:43] op_sel_hi:[0,1,1]
	v_pk_fma_f32 v[44:45], v[228:229], v[56:57], v[44:45] op_sel_hi:[0,1,1]
	s_waitcnt vmcnt(10)
	v_pk_fma_f32 v[38:39], v[228:229], v[58:59], v[38:39] op_sel:[1,0,0] op_sel_hi:[1,1,1]
	v_pk_fma_f32 v[40:41], v[228:229], v[60:61], v[40:41] op_sel:[1,0,0] op_sel_hi:[1,1,1]
	v_pk_fma_f32 v[42:43], v[228:229], v[62:63], v[42:43] op_sel:[1,0,0] op_sel_hi:[1,1,1]
	v_pk_fma_f32 v[44:45], v[228:229], v[64:65], v[44:45] op_sel:[1,0,0] op_sel_hi:[1,1,1]
	s_waitcnt vmcnt(9)
	v_pk_fma_f32 v[38:39], v[230:231], v[66:67], v[38:39] op_sel_hi:[0,1,1]
	v_pk_fma_f32 v[40:41], v[230:231], v[68:69], v[40:41] op_sel_hi:[0,1,1]
	v_pk_fma_f32 v[42:43], v[230:231], v[70:71], v[42:43] op_sel_hi:[0,1,1]
	v_pk_fma_f32 v[44:45], v[230:231], v[72:73], v[44:45] op_sel_hi:[0,1,1]
	s_waitcnt vmcnt(8)
	v_pk_fma_f32 v[38:39], v[230:231], v[74:75], v[38:39] op_sel:[1,0,0] op_sel_hi:[1,1,1]
	v_pk_fma_f32 v[40:41], v[230:231], v[76:77], v[40:41] op_sel:[1,0,0] op_sel_hi:[1,1,1]
	v_pk_fma_f32 v[42:43], v[230:231], v[78:79], v[42:43] op_sel:[1,0,0] op_sel_hi:[1,1,1]
	v_pk_fma_f32 v[44:45], v[230:231], v[80:81], v[44:45] op_sel:[1,0,0] op_sel_hi:[1,1,1]
	s_waitcnt vmcnt(7)
	v_pk_fma_f32 v[38:39], v[232:233], v[82:83], v[38:39] op_sel_hi:[0,1,1]
	v_pk_fma_f32 v[40:41], v[232:233], v[84:85], v[40:41] op_sel_hi:[0,1,1]
	v_pk_fma_f32 v[42:43], v[232:233], v[86:87], v[42:43] op_sel_hi:[0,1,1]
	v_pk_fma_f32 v[44:45], v[232:233], v[88:89], v[44:45] op_sel_hi:[0,1,1]
	s_waitcnt vmcnt(6)
	v_pk_fma_f32 v[38:39], v[232:233], v[90:91], v[38:39] op_sel:[1,0,0] op_sel_hi:[1,1,1]
	v_pk_fma_f32 v[40:41], v[232:233], v[92:93], v[40:41] op_sel:[1,0,0] op_sel_hi:[1,1,1]
	v_pk_fma_f32 v[42:43], v[232:233], v[94:95], v[42:43] op_sel:[1,0,0] op_sel_hi:[1,1,1]
	v_pk_fma_f32 v[44:45], v[232:233], v[96:97], v[44:45] op_sel:[1,0,0] op_sel_hi:[1,1,1]
	s_waitcnt vmcnt(5)
	v_pk_fma_f32 v[38:39], v[234:235], v[98:99], v[38:39] op_sel_hi:[0,1,1]
	v_pk_fma_f32 v[40:41], v[234:235], v[100:101], v[40:41] op_sel_hi:[0,1,1]
	v_pk_fma_f32 v[42:43], v[234:235], v[102:103], v[42:43] op_sel_hi:[0,1,1]
	v_pk_fma_f32 v[44:45], v[234:235], v[104:105], v[44:45] op_sel_hi:[0,1,1]
	s_waitcnt vmcnt(4)
	v_pk_fma_f32 v[38:39], v[234:235], v[106:107], v[38:39] op_sel:[1,0,0] op_sel_hi:[1,1,1]
	v_pk_fma_f32 v[40:41], v[234:235], v[108:109], v[40:41] op_sel:[1,0,0] op_sel_hi:[1,1,1]
	v_pk_fma_f32 v[42:43], v[234:235], v[110:111], v[42:43] op_sel:[1,0,0] op_sel_hi:[1,1,1]
	v_pk_fma_f32 v[44:45], v[234:235], v[112:113], v[44:45] op_sel:[1,0,0] op_sel_hi:[1,1,1]
	s_waitcnt vmcnt(3)
	v_pk_fma_f32 v[38:39], v[236:237], v[114:115], v[38:39] op_sel_hi:[0,1,1]
	v_pk_fma_f32 v[40:41], v[236:237], v[116:117], v[40:41] op_sel_hi:[0,1,1]
	v_pk_fma_f32 v[42:43], v[236:237], v[118:119], v[42:43] op_sel_hi:[0,1,1]
	v_pk_fma_f32 v[44:45], v[236:237], v[120:121], v[44:45] op_sel_hi:[0,1,1]
	s_waitcnt vmcnt(2)
	v_pk_fma_f32 v[38:39], v[236:237], v[122:123], v[38:39] op_sel:[1,0,0] op_sel_hi:[1,1,1]
	v_pk_fma_f32 v[40:41], v[236:237], v[124:125], v[40:41] op_sel:[1,0,0] op_sel_hi:[1,1,1]
	v_pk_fma_f32 v[42:43], v[236:237], v[126:127], v[42:43] op_sel:[1,0,0] op_sel_hi:[1,1,1]
	v_pk_fma_f32 v[44:45], v[236:237], v[128:129], v[44:45] op_sel:[1,0,0] op_sel_hi:[1,1,1]
	s_waitcnt vmcnt(1)
	v_pk_fma_f32 v[38:39], v[238:239], v[130:131], v[38:39] op_sel_hi:[0,1,1]
	v_pk_fma_f32 v[40:41], v[238:239], v[132:133], v[40:41] op_sel_hi:[0,1,1]
	v_pk_fma_f32 v[42:43], v[238:239], v[134:135], v[42:43] op_sel_hi:[0,1,1]
	v_pk_fma_f32 v[44:45], v[238:239], v[136:137], v[44:45] op_sel_hi:[0,1,1]
	s_waitcnt vmcnt(0)
	v_pk_fma_f32 v[38:39], v[238:239], v[138:139], v[38:39] op_sel:[1,0,0] op_sel_hi:[1,1,1]
	v_pk_fma_f32 v[40:41], v[238:239], v[140:141], v[40:41] op_sel:[1,0,0] op_sel_hi:[1,1,1]
	v_pk_fma_f32 v[42:43], v[238:239], v[142:143], v[42:43] op_sel:[1,0,0] op_sel_hi:[1,1,1]
	v_pk_fma_f32 v[44:45], v[238:239], v[144:145], v[44:45] op_sel:[1,0,0] op_sel_hi:[1,1,1]
	v_mbcnt_lo_u32_b32 v2, -1, 0
	v_mbcnt_hi_u32_b32 v2, -1, v2
	v_and_b32_e32 v4, 64, v2
	v_xor_b32_e32 v3, 32, v2
	v_add_u32_e32 v4, 64, v4
	v_cmp_lt_i32_e32 vcc, v3, v4
	s_nop 1
	v_cndmask_b32_e32 v2, v2, v3, vcc
	v_lshlrev_b32_e32 v9, 2, v2
	ds_bpermute_b32 v2, v9, v38
	ds_bpermute_b32 v3, v9, v39
	ds_bpermute_b32 v4, v9, v40
	ds_bpermute_b32 v5, v9, v41
	ds_bpermute_b32 v6, v9, v42
	ds_bpermute_b32 v7, v9, v43
	ds_bpermute_b32 v8, v9, v44
	ds_bpermute_b32 v9, v9, v45
	v_cmp_gt_u32_e32 vcc, 32, v1
	s_and_saveexec_b64 s[38:39], vcc
	s_cbranch_execz .LBB0_17
	s_lshl_b32 s1, s99, 10
	s_add_i32 s1, s1, 0
	v_lshl_add_u32 v10, v1, 2, s1
	s_waitcnt lgkmcnt(6)
	v_add_f32_e32 v3, v39, v3
	v_add_f32_e32 v2, v38, v2
	v_add_u32_e32 v10, 0x8000, v10
	s_waitcnt lgkmcnt(0)
	v_add_f32_e32 v9, v45, v9
	v_add_f32_e32 v8, v44, v8
	v_add_f32_e32 v7, v43, v7
	v_add_f32_e32 v6, v42, v6
	v_add_f32_e32 v5, v41, v5
	v_add_f32_e32 v4, v40, v4
	ds_write2_b32 v10, v2, v3 offset1:32
	ds_write2_b32 v10, v4, v5 offset0:64 offset1:96
	ds_write2_b32 v10, v6, v7 offset0:128 offset1:160
	ds_write2_b32 v10, v8, v9 offset0:192 offset1:224
.LBB0_17:
	s_or_b64 exec, exec, s[38:39]
	s_waitcnt lgkmcnt(0)
	s_barrier
	s_and_saveexec_b64 s[38:39], s[4:5]
	s_cbranch_execz .LBB0_35
	v_or_b32_e32 v2, s6, v48
	v_mov_b32_e32 v4, s42
	v_mov_b32_e32 v5, s43
	v_ashrrev_i32_e32 v3, 31, v2
	v_lshl_add_u64 v[4:5], v[2:3], 2, v[4:5]
	v_mov_b32_e32 v12, v242
	v_and_b32_e32 v4, 0xe0, v0
	v_lshlrev_b32_e32 v4, 2, v4
	v_add3_u32 v10, 0, v4, v34
	ds_read2st64_b32 v[4:5], v10 offset0:128 offset1:132
	ds_read2st64_b32 v[6:7], v10 offset0:136 offset1:140
	ds_read2st64_b32 v[8:9], v10 offset0:144 offset1:148
	ds_read2st64_b32 v[10:11], v10 offset0:152 offset1:156
	s_ashr_i32 s0, s0, 5
	v_mov_b32_e32 v13, 0x3ff
	s_cmp_lt_i32 s0, 4
	s_waitcnt lgkmcnt(3)
	v_add_f32_e32 v4, 0, v4
	v_add_f32_e32 v4, v4, v5
	s_waitcnt lgkmcnt(2)
	v_add_f32_e32 v4, v4, v6
	v_add_f32_e32 v4, v4, v7
	s_waitcnt lgkmcnt(1)
	v_add_f32_e32 v4, v4, v8
	v_add_f32_e32 v4, v4, v9
	s_waitcnt lgkmcnt(0)
	v_add_f32_e32 v4, v4, v10
	v_add_f32_e32 v4, v4, v11
	v_bitop3_b32 v5, s6, v13, v48 bitop3:0xc8
	s_waitcnt vmcnt(0)
	v_add_f32_e32 v4, v4, v12
	s_cbranch_scc1 .LBB0_21
	s_cmp_gt_i32 s0, 4
	s_cbranch_scc0 .LBB0_22
	v_readlane_b32 s24, v250, 0
	v_lshlrev_b32_e32 v6, 2, v5
	v_readlane_b32 s25, v250, 1
	v_readlane_b32 s26, v250, 2
	v_readlane_b32 s27, v250, 3
	v_readlane_b32 s28, v250, 4
	v_readlane_b32 s29, v250, 5
	v_readlane_b32 s30, v250, 6
	v_mov_b32_e32 v6, v243
	v_readlane_b32 s31, v250, 7
	s_mov_b64 s[4:5], 0
	s_waitcnt vmcnt(0)
	v_mul_f32_e32 v6, v4, v6
	s_branch .LBB0_23

.LBB0_23:
	s_andn2_b64 vcc, exec, s[4:5]
	s_cbranch_vccnz .LBB0_25
	v_lshlrev_b32_e32 v6, 2, v5
	v_mov_b32_e32 v6, v243
	v_add_f32_e32 v7, 1.0, v4
	s_waitcnt vmcnt(0)
	v_mul_f32_e32 v6, v7, v6

.LBB0_26:
	s_cmp_lt_i32 s0, 2
	s_cbranch_scc1 .LBB0_29
	s_cmp_eq_u32 s0, 2
	v_mov_b32_e32 v6, v4
	s_cbranch_scc0 .LBB0_30
	v_lshlrev_b32_e32 v6, 2, v5
	v_mov_b32_e32 v6, v243
	s_waitcnt vmcnt(0)
	v_mul_f32_e32 v6, v4, v6
	s_cbranch_execz .LBB0_31
	s_branch .LBB0_34

.LBB0_31:
	s_cmp_lg_u32 s0, 1
	s_cbranch_scc1 .LBB0_33
	v_lshlrev_b32_e32 v5, 2, v5
	v_mov_b32_e32 v5, v243
	v_add_f32_e32 v4, 1.0, v4
	s_waitcnt vmcnt(0)
	v_mul_f32_e32 v4, v4, v5

.LBB0_54:
	s_cmpk_lt_i32 s2, 0xc0
	s_cbranch_scc1 .LBB0_60
	s_lshl_b32 s0, s2, 3
	s_add_i32 s0, s0, s99
	s_addk_i32 s0, 0xfa00
	s_cmpk_gt_i32 s0, 0x4ff
	s_cbranch_scc1 .LBB0_60
	s_lshl_b32 s1, s99, 14
	v_and_b32_e32 v2, 31, v0
	s_add_i32 s1, s1, 0
	v_lshlrev_b32_e32 v4, 2, v2
	v_mov_b32_e32 v5, 0
	v_lshrrev_b32_e32 v6, 5, v1
	v_lshl_add_u64 v[2:3], s[48:49], 0, v[4:5]
	v_add_u32_e32 v13, s1, v4
	v_lshlrev_b32_e32 v4, 3, v0
	v_mul_u32_u24_e32 v14, 0x84, v6
	v_lshrrev_b32_e32 v7, 3, v1
	v_and_b32_e32 v4, 56, v4
	v_mul_u32_u24_e32 v8, 0x84, v4
	v_lshlrev_b32_e32 v4, 1, v4
	v_lshlrev_b32_e32 v9, 2, v7
	v_add_u32_e32 v13, v13, v14
	v_lshl_add_u64 v[4:5], s[70:71], 0, v[4:5]
	v_add3_u32 v8, s1, v8, v9
	v_or_b32_e32 v9, 8, v7
	v_or_b32_e32 v10, 16, v7
	v_or_b32_e32 v11, 24, v7
	s_lshl_b32 s1, s0, 5
	s_lshl_b32 s3, s0, 6
	v_mov_b32_e32 v12, 0x3fb8aa3b
	s_movk_i32 s22, 0x2800
	v_add_u32_e32 v14, 0x400, v13
	v_add_u32_e32 v15, 0x800, v13
	v_add_u32_e32 v16, 0xc00, v13
	v_add_u32_e32 v17, 0x1000, v13
	v_add_u32_e32 v18, 0x1400, v13
	v_add_u32_e32 v19, 0x1800, v13
	v_add_u32_e32 v20, 0x1c00, v13
	s_mul_hi_i32 s4, s0, 0x66666667
	s_lshr_b32 s5, s4, 31
	s_ashr_i32 s4, s4, 5
	s_add_i32 s4, s4, s5
	s_mul_i32 s5, s4, 0xffffffb0
	s_mul_i32 s6, s4, 0xfffff600
	s_add_i32 s5, s0, s5
	s_add_i32 s6, s1, s6
	s_cmp_lt_i32 s5, 16
	s_mov_b32 s23, s6
	s_cbranch_scc1 .Lcv_hdr0
	s_add_i32 s7, s6, 0xfffffe00
	s_and_b32 s23, s6, 0x60
	s_and_b32 s25, s3, 0x300
	s_and_b32 s24, s7, 0xfffffc00
	s_lshr_b32 s7, s7, 2
	s_or_b32 s23, s25, s23
	s_and_b32 s7, s7, 0x80
	s_or_b32 s23, s23, s24
	s_or_b32 s7, s23, s7
	s_add_i32 s23, s7, 0x200
.Lcv_hdr0:
	s_cmp_gt_i32 s5, 63
	s_cselect_b64 vcc, -1, 0
	s_lshl_b32 s4, s4, 6
	v_or_b32_e32 v40, s4, v6
	s_ashr_i32 s7, s6, 31
	v_lshl_add_u64 v[22:23], s[6:7], 2, v[2:3]
	v_or_b32_e32 v26, 2, v40
	v_or_b32_e32 v28, 4, v40
	v_or_b32_e32 v30, 6, v40
	v_or_b32_e32 v32, 8, v40
	v_or_b32_e32 v34, 10, v40
	v_or_b32_e32 v36, 12, v40
	v_or_b32_e32 v38, 14, v40
	v_mad_i64_i32 v[24:25], s[6:7], v40, s22, v[22:23]
	v_mad_i64_i32 v[26:27], s[6:7], v26, s22, v[22:23]
	v_mad_i64_i32 v[28:29], s[6:7], v28, s22, v[22:23]
	v_mad_i64_i32 v[30:31], s[6:7], v30, s22, v[22:23]
	v_mad_i64_i32 v[32:33], s[6:7], v32, s22, v[22:23]
	v_mad_i64_i32 v[34:35], s[6:7], v34, s22, v[22:23]
	v_mad_i64_i32 v[36:37], s[6:7], v36, s22, v[22:23]
	v_mad_i64_i32 v[38:39], s[6:7], v38, s22, v[22:23]
	global_load_dword v41, v[24:25], off nt
	global_load_dword v42, v[26:27], off nt
	global_load_dword v43, v[28:29], off nt
	global_load_dword v44, v[30:31], off nt
	global_load_dword v45, v[32:33], off nt
	global_load_dword v46, v[34:35], off nt
	global_load_dword v47, v[36:37], off nt
	global_load_dword v48, v[38:39], off nt
	v_or_b32_e32 v24, 16, v40
	v_or_b32_e32 v26, 18, v40
	v_or_b32_e32 v28, 20, v40
	v_or_b32_e32 v30, 22, v40
	v_or_b32_e32 v32, 24, v40
	v_or_b32_e32 v34, 26, v40
	v_or_b32_e32 v36, 28, v40
	v_or_b32_e32 v38, 30, v40
	v_mad_i64_i32 v[24:25], s[6:7], v24, s22, v[22:23]
	v_mad_i64_i32 v[26:27], s[6:7], v26, s22, v[22:23]
	v_mad_i64_i32 v[28:29], s[6:7], v28, s22, v[22:23]
	v_mad_i64_i32 v[30:31], s[6:7], v30, s22, v[22:23]
	v_mad_i64_i32 v[32:33], s[6:7], v32, s22, v[22:23]
	v_mad_i64_i32 v[34:35], s[6:7], v34, s22, v[22:23]
	v_mad_i64_i32 v[36:37], s[6:7], v36, s22, v[22:23]
	v_mad_i64_i32 v[38:39], s[6:7], v38, s22, v[22:23]
	global_load_dword v49, v[24:25], off nt
	global_load_dword v50, v[26:27], off nt
	global_load_dword v51, v[28:29], off nt
	global_load_dword v52, v[30:31], off nt
	global_load_dword v53, v[32:33], off nt
	global_load_dword v54, v[34:35], off nt
	global_load_dword v55, v[36:37], off nt
	global_load_dword v56, v[38:39], off nt
	v_or_b32_e32 v24, 32, v40
	v_or_b32_e32 v26, 34, v40
	v_or_b32_e32 v28, 36, v40
	v_or_b32_e32 v30, 38, v40
	v_or_b32_e32 v32, 40, v40
	v_or_b32_e32 v34, 42, v40
	v_or_b32_e32 v36, 44, v40
	v_or_b32_e32 v38, 46, v40
	v_mad_i64_i32 v[24:25], s[6:7], v24, s22, v[22:23]
	v_mad_i64_i32 v[26:27], s[6:7], v26, s22, v[22:23]
	v_mad_i64_i32 v[28:29], s[6:7], v28, s22, v[22:23]
	v_mad_i64_i32 v[30:31], s[6:7], v30, s22, v[22:23]
	v_mad_i64_i32 v[32:33], s[6:7], v32, s22, v[22:23]
	v_mad_i64_i32 v[34:35], s[6:7], v34, s22, v[22:23]
	v_mad_i64_i32 v[36:37], s[6:7], v36, s22, v[22:23]
	v_mad_i64_i32 v[38:39], s[6:7], v38, s22, v[22:23]
	global_load_dword v57, v[24:25], off nt
	global_load_dword v58, v[26:27], off nt
	global_load_dword v59, v[28:29], off nt
	global_load_dword v60, v[30:31], off nt
	global_load_dword v61, v[32:33], off nt
	global_load_dword v62, v[34:35], off nt
	global_load_dword v63, v[36:37], off nt
	s_nop 0
	global_load_dword v72, v[38:39], off nt
	v_or_b32_e32 v24, 48, v40
	v_or_b32_e32 v26, 50, v40
	v_or_b32_e32 v28, 52, v40
	v_or_b32_e32 v30, 54, v40
	v_or_b32_e32 v32, 56, v40
	v_or_b32_e32 v34, 58, v40
	v_or_b32_e32 v36, 60, v40
	v_or_b32_e32 v39, 62, v40
	v_mad_i64_i32 v[24:25], s[6:7], v24, s22, v[22:23]
	v_mad_i64_i32 v[26:27], s[6:7], v26, s22, v[22:23]
	v_mad_i64_i32 v[28:29], s[6:7], v28, s22, v[22:23]
	v_mad_i64_i32 v[30:31], s[6:7], v30, s22, v[22:23]
	v_mad_i64_i32 v[32:33], s[6:7], v32, s22, v[22:23]
	v_mad_i64_i32 v[34:35], s[6:7], v34, s22, v[22:23]
	v_mad_i64_i32 v[36:37], s[6:7], v36, s22, v[22:23]
	v_mad_i64_i32 v[22:23], s[6:7], v39, s22, v[22:23]
	global_load_dword v64, v[24:25], off nt
	s_nop 0
	global_load_dword v65, v[26:27], off nt
	s_nop 0
	global_load_dword v66, v[28:29], off nt
	global_load_dword v67, v[30:31], off nt
	s_nop 0
	global_load_dword v68, v[32:33], off nt
	global_load_dword v69, v[34:35], off nt
	global_load_dword v70, v[36:37], off nt
	s_nop 0
	global_load_dword v71, v[22:23], off nt
	s_waitcnt vmcnt(30)
	ds_write2_b32 v13, v41, v42 offset1:66
	s_waitcnt vmcnt(28)
	ds_write2_b32 v13, v43, v44 offset0:132 offset1:198
	s_waitcnt vmcnt(26)
	ds_write2_b32 v14, v45, v46 offset0:8 offset1:74
	s_waitcnt vmcnt(24)
	ds_write2_b32 v14, v47, v48 offset0:140 offset1:206
	s_waitcnt vmcnt(22)
	ds_write2_b32 v15, v49, v50 offset0:16 offset1:82
	s_waitcnt vmcnt(20)
	ds_write2_b32 v15, v51, v52 offset0:148 offset1:214
	s_waitcnt vmcnt(18)
	ds_write2_b32 v16, v53, v54 offset0:24 offset1:90
	s_waitcnt vmcnt(16)
	ds_write2_b32 v16, v55, v56 offset0:156 offset1:222
	s_waitcnt vmcnt(14)
	ds_write2_b32 v17, v57, v58 offset0:32 offset1:98
	s_waitcnt vmcnt(12)
	ds_write2_b32 v17, v59, v60 offset0:164 offset1:230
	s_waitcnt vmcnt(10)
	ds_write2_b32 v18, v61, v62 offset0:40 offset1:106
	s_waitcnt vmcnt(8)
	ds_write2_b32 v18, v63, v72 offset0:172 offset1:238
	s_waitcnt vmcnt(6)
	ds_write2_b32 v19, v64, v65 offset0:48 offset1:114
	s_waitcnt vmcnt(4)
	ds_write2_b32 v19, v66, v67 offset0:180 offset1:246
	s_waitcnt vmcnt(2)
	ds_write2_b32 v20, v68, v69 offset0:56 offset1:122
	s_waitcnt vmcnt(0)
	ds_write2_b32 v20, v70, v71 offset0:188 offset1:254
	s_branch .Lcv_after_b
.Lcv_loop:
	s_waitcnt vmcnt(34)
	ds_write2_b32 v13, v41, v42 offset1:66
	s_waitcnt vmcnt(32)
	ds_write2_b32 v13, v43, v44 offset0:132 offset1:198
	s_waitcnt vmcnt(30)
	ds_write2_b32 v14, v45, v46 offset0:8 offset1:74
	s_waitcnt vmcnt(28)
	ds_write2_b32 v14, v47, v48 offset0:140 offset1:206
	s_waitcnt vmcnt(26)
	ds_write2_b32 v15, v49, v50 offset0:16 offset1:82
	s_waitcnt vmcnt(24)
	ds_write2_b32 v15, v51, v52 offset0:148 offset1:214
	s_waitcnt vmcnt(22)
	ds_write2_b32 v16, v53, v54 offset0:24 offset1:90
	s_waitcnt vmcnt(20)
	ds_write2_b32 v16, v55, v56 offset0:156 offset1:222
	s_waitcnt vmcnt(18)
	ds_write2_b32 v17, v57, v58 offset0:32 offset1:98
	s_waitcnt vmcnt(16)
	ds_write2_b32 v17, v59, v60 offset0:164 offset1:230
	s_waitcnt vmcnt(14)
	ds_write2_b32 v18, v61, v62 offset0:40 offset1:106
	s_waitcnt vmcnt(12)
	ds_write2_b32 v18, v63, v72 offset0:172 offset1:238
	s_waitcnt vmcnt(10)
	ds_write2_b32 v19, v64, v65 offset0:48 offset1:114
	s_waitcnt vmcnt(8)
	ds_write2_b32 v19, v66, v67 offset0:180 offset1:246
	s_waitcnt vmcnt(6)
	ds_write2_b32 v20, v68, v69 offset0:56 offset1:122
	s_waitcnt vmcnt(4)
	ds_write2_b32 v20, v70, v71 offset0:188 offset1:254
.Lcv_after_b:
	s_waitcnt lgkmcnt(0)
	v_cndmask_b32_e32 v21, 1.0, v12, vcc
	s_ashr_i32 s5, s4, 31
	v_lshl_add_u64 v[74:75], s[4:5], 1, v[4:5]
	s_mov_b32 s98, s23
	s_cmpk_gt_i32 s0, 0x2ff
	s_cselect_b32 s32, 0, 1
	s_add_i32 s0, s0, 0x200
	s_addk_i32 s1, 0x4000
	s_add_i32 s3, s3, 0x8000
	s_cmp_eq_u32 s32, 0
	s_cbranch_scc1 .Lcv_nonext
	s_mul_hi_i32 s4, s0, 0x66666667
	s_lshr_b32 s5, s4, 31
	s_ashr_i32 s4, s4, 5
	s_add_i32 s4, s4, s5
	s_mul_i32 s5, s4, 0xffffffb0
	s_mul_i32 s6, s4, 0xfffff600
	s_add_i32 s5, s0, s5
	s_add_i32 s6, s1, s6
	s_cmp_lt_i32 s5, 16
	s_mov_b32 s23, s6
	s_cbranch_scc1 .Lcv_hdr1
	s_add_i32 s7, s6, 0xfffffe00
	s_and_b32 s23, s6, 0x60
	s_and_b32 s25, s3, 0x300
	s_and_b32 s24, s7, 0xfffffc00
	s_lshr_b32 s7, s7, 2
	s_or_b32 s23, s25, s23
	s_and_b32 s7, s7, 0x80
	s_or_b32 s23, s23, s24
	s_or_b32 s7, s23, s7
	s_add_i32 s23, s7, 0x200
.Lcv_hdr1:
	s_cmp_gt_i32 s5, 63
	s_cselect_b64 vcc, -1, 0
	s_lshl_b32 s4, s4, 6
	v_or_b32_e32 v40, s4, v6
	s_ashr_i32 s7, s6, 31
	v_lshl_add_u64 v[22:23], s[6:7], 2, v[2:3]
	v_or_b32_e32 v26, 2, v40
	v_or_b32_e32 v28, 4, v40
	v_or_b32_e32 v30, 6, v40
	v_or_b32_e32 v32, 8, v40
	v_or_b32_e32 v34, 10, v40
	v_or_b32_e32 v36, 12, v40
	v_or_b32_e32 v38, 14, v40
	v_mad_i64_i32 v[24:25], s[6:7], v40, s22, v[22:23]
	v_mad_i64_i32 v[26:27], s[6:7], v26, s22, v[22:23]
	v_mad_i64_i32 v[28:29], s[6:7], v28, s22, v[22:23]
	v_mad_i64_i32 v[30:31], s[6:7], v30, s22, v[22:23]
	v_mad_i64_i32 v[32:33], s[6:7], v32, s22, v[22:23]
	v_mad_i64_i32 v[34:35], s[6:7], v34, s22, v[22:23]
	v_mad_i64_i32 v[36:37], s[6:7], v36, s22, v[22:23]
	v_mad_i64_i32 v[38:39], s[6:7], v38, s22, v[22:23]
	global_load_dword v41, v[24:25], off nt
	global_load_dword v42, v[26:27], off nt
	global_load_dword v43, v[28:29], off nt
	global_load_dword v44, v[30:31], off nt
	global_load_dword v45, v[32:33], off nt
	global_load_dword v46, v[34:35], off nt
	global_load_dword v47, v[36:37], off nt
	global_load_dword v48, v[38:39], off nt
	v_or_b32_e32 v24, 16, v40
	v_or_b32_e32 v26, 18, v40
	v_or_b32_e32 v28, 20, v40
	v_or_b32_e32 v30, 22, v40
	v_or_b32_e32 v32, 24, v40
	v_or_b32_e32 v34, 26, v40
	v_or_b32_e32 v36, 28, v40
	v_or_b32_e32 v38, 30, v40
	v_mad_i64_i32 v[24:25], s[6:7], v24, s22, v[22:23]
	v_mad_i64_i32 v[26:27], s[6:7], v26, s22, v[22:23]
	v_mad_i64_i32 v[28:29], s[6:7], v28, s22, v[22:23]
	v_mad_i64_i32 v[30:31], s[6:7], v30, s22, v[22:23]
	v_mad_i64_i32 v[32:33], s[6:7], v32, s22, v[22:23]
	v_mad_i64_i32 v[34:35], s[6:7], v34, s22, v[22:23]
	v_mad_i64_i32 v[36:37], s[6:7], v36, s22, v[22:23]
	v_mad_i64_i32 v[38:39], s[6:7], v38, s22, v[22:23]
	global_load_dword v49, v[24:25], off nt
	global_load_dword v50, v[26:27], off nt
	global_load_dword v51, v[28:29], off nt
	global_load_dword v52, v[30:31], off nt
	global_load_dword v53, v[32:33], off nt
	global_load_dword v54, v[34:35], off nt
	global_load_dword v55, v[36:37], off nt
	global_load_dword v56, v[38:39], off nt
	v_or_b32_e32 v24, 32, v40
	v_or_b32_e32 v26, 34, v40
	v_or_b32_e32 v28, 36, v40
	v_or_b32_e32 v30, 38, v40
	v_or_b32_e32 v32, 40, v40
	v_or_b32_e32 v34, 42, v40
	v_or_b32_e32 v36, 44, v40
	v_or_b32_e32 v38, 46, v40
	v_mad_i64_i32 v[24:25], s[6:7], v24, s22, v[22:23]
	v_mad_i64_i32 v[26:27], s[6:7], v26, s22, v[22:23]
	v_mad_i64_i32 v[28:29], s[6:7], v28, s22, v[22:23]
	v_mad_i64_i32 v[30:31], s[6:7], v30, s22, v[22:23]
	v_mad_i64_i32 v[32:33], s[6:7], v32, s22, v[22:23]
	v_mad_i64_i32 v[34:35], s[6:7], v34, s22, v[22:23]
	v_mad_i64_i32 v[36:37], s[6:7], v36, s22, v[22:23]
	v_mad_i64_i32 v[38:39], s[6:7], v38, s22, v[22:23]
	global_load_dword v57, v[24:25], off nt
	global_load_dword v58, v[26:27], off nt
	global_load_dword v59, v[28:29], off nt
	global_load_dword v60, v[30:31], off nt
	global_load_dword v61, v[32:33], off nt
	global_load_dword v62, v[34:35], off nt
	global_load_dword v63, v[36:37], off nt
	s_nop 0
	global_load_dword v72, v[38:39], off nt
	v_or_b32_e32 v24, 48, v40
	v_or_b32_e32 v26, 50, v40
	v_or_b32_e32 v28, 52, v40
	v_or_b32_e32 v30, 54, v40
	v_or_b32_e32 v32, 56, v40
	v_or_b32_e32 v34, 58, v40
	v_or_b32_e32 v36, 60, v40
	v_or_b32_e32 v39, 62, v40
	v_mad_i64_i32 v[24:25], s[6:7], v24, s22, v[22:23]
	v_mad_i64_i32 v[26:27], s[6:7], v26, s22, v[22:23]
	v_mad_i64_i32 v[28:29], s[6:7], v28, s22, v[22:23]
	v_mad_i64_i32 v[30:31], s[6:7], v30, s22, v[22:23]
	v_mad_i64_i32 v[32:33], s[6:7], v32, s22, v[22:23]
	v_mad_i64_i32 v[34:35], s[6:7], v34, s22, v[22:23]
	v_mad_i64_i32 v[36:37], s[6:7], v36, s22, v[22:23]
	v_mad_i64_i32 v[22:23], s[6:7], v39, s22, v[22:23]
	global_load_dword v64, v[24:25], off nt
	s_nop 0
	global_load_dword v65, v[26:27], off nt
	s_nop 0
	global_load_dword v66, v[28:29], off nt
	global_load_dword v67, v[30:31], off nt
	s_nop 0
	global_load_dword v68, v[32:33], off nt
	global_load_dword v69, v[34:35], off nt
	global_load_dword v70, v[36:37], off nt
	s_nop 0
	global_load_dword v71, v[22:23], off nt
.Lcv_nonext:
	ds_read2_b32 v[22:23], v8 offset1:33
	s_waitcnt lgkmcnt(0)
	v_mul_f32_e32 v22, v21, v22
	v_mul_f32_e32 v23, v21, v23
	v_cvt_pk_bf16_f32 v22, v22, v23
	ds_read2_b32 v[24:25], v8 offset0:66 offset1:99
	s_waitcnt lgkmcnt(0)
	v_mul_f32_e32 v23, v21, v24
	v_mul_f32_e32 v24, v21, v25
	v_cvt_pk_bf16_f32 v23, v23, v24
	ds_read2_b32 v[24:25], v8 offset0:132 offset1:165
	s_waitcnt lgkmcnt(0)
	v_mul_f32_e32 v24, v21, v24
	v_mul_f32_e32 v25, v21, v25
	v_cvt_pk_bf16_f32 v24, v24, v25
	ds_read2_b32 v[26:27], v8 offset0:198 offset1:231
	s_waitcnt lgkmcnt(0)
	v_mul_f32_e32 v25, v21, v26
	v_mul_f32_e32 v26, v21, v27
	v_cvt_pk_bf16_f32 v25, v25, v26
	v_add_u32_e32 v26, s98, v7
	v_ashrrev_i32_e32 v27, 31, v26
	v_lshlrev_b64 v[26:27], 11, v[26:27]
	v_lshl_add_u64 v[26:27], v[74:75], 0, v[26:27]
	global_store_dwordx4 v[26:27], v[22:25], off sc1
	s_nop 1
	ds_read2_b32 v[22:23], v8 offset0:8 offset1:41
	s_waitcnt lgkmcnt(0)
	v_mul_f32_e32 v22, v21, v22
	v_mul_f32_e32 v23, v21, v23
	v_cvt_pk_bf16_f32 v22, v22, v23
	ds_read2_b32 v[24:25], v8 offset0:74 offset1:107
	s_waitcnt lgkmcnt(0)
	v_mul_f32_e32 v23, v21, v24
	v_mul_f32_e32 v24, v21, v25
	v_cvt_pk_bf16_f32 v23, v23, v24
	ds_read2_b32 v[24:25], v8 offset0:140 offset1:173
	s_waitcnt lgkmcnt(0)
	v_mul_f32_e32 v24, v21, v24
	v_mul_f32_e32 v25, v21, v25
	v_cvt_pk_bf16_f32 v24, v24, v25
	ds_read2_b32 v[26:27], v8 offset0:206 offset1:239
	s_waitcnt lgkmcnt(0)
	v_mul_f32_e32 v25, v21, v26
	v_mul_f32_e32 v26, v21, v27
	v_cvt_pk_bf16_f32 v25, v25, v26
	v_add_u32_e32 v26, s98, v9
	v_ashrrev_i32_e32 v27, 31, v26
	v_lshlrev_b64 v[26:27], 11, v[26:27]
	v_lshl_add_u64 v[26:27], v[74:75], 0, v[26:27]
	global_store_dwordx4 v[26:27], v[22:25], off sc1
	s_nop 1
	ds_read2_b32 v[22:23], v8 offset0:16 offset1:49
	s_waitcnt lgkmcnt(0)
	v_mul_f32_e32 v22, v21, v22
	v_mul_f32_e32 v23, v21, v23
	v_cvt_pk_bf16_f32 v22, v22, v23
	ds_read2_b32 v[24:25], v8 offset0:82 offset1:115
	s_waitcnt lgkmcnt(0)
	v_mul_f32_e32 v23, v21, v24
	v_mul_f32_e32 v24, v21, v25
	v_cvt_pk_bf16_f32 v23, v23, v24
	ds_read2_b32 v[24:25], v8 offset0:148 offset1:181
	s_waitcnt lgkmcnt(0)
	v_mul_f32_e32 v24, v21, v24
	v_mul_f32_e32 v25, v21, v25
	v_cvt_pk_bf16_f32 v24, v24, v25
	ds_read2_b32 v[26:27], v8 offset0:214 offset1:247
	s_waitcnt lgkmcnt(0)
	v_mul_f32_e32 v25, v21, v26
	v_mul_f32_e32 v26, v21, v27
	v_cvt_pk_bf16_f32 v25, v25, v26
	v_add_u32_e32 v26, s98, v10
	v_ashrrev_i32_e32 v27, 31, v26
	v_lshlrev_b64 v[26:27], 11, v[26:27]
	v_lshl_add_u64 v[26:27], v[74:75], 0, v[26:27]
	global_store_dwordx4 v[26:27], v[22:25], off sc1
	s_nop 1
	ds_read2_b32 v[22:23], v8 offset0:24 offset1:57
	s_waitcnt lgkmcnt(0)
	v_mul_f32_e32 v22, v21, v22
	v_mul_f32_e32 v23, v21, v23
	v_cvt_pk_bf16_f32 v22, v22, v23
	ds_read2_b32 v[24:25], v8 offset0:90 offset1:123
	s_waitcnt lgkmcnt(0)
	v_mul_f32_e32 v23, v21, v24
	v_mul_f32_e32 v24, v21, v25
	v_cvt_pk_bf16_f32 v23, v23, v24
	ds_read2_b32 v[24:25], v8 offset0:156 offset1:189
	s_waitcnt lgkmcnt(0)
	v_mul_f32_e32 v24, v21, v24
	v_mul_f32_e32 v25, v21, v25
	v_cvt_pk_bf16_f32 v24, v24, v25
	ds_read2_b32 v[26:27], v8 offset0:222 offset1:255
	s_waitcnt lgkmcnt(0)
	v_mul_f32_e32 v25, v21, v26
	v_add_u32_e32 v26, s98, v11
	v_mul_f32_e32 v21, v21, v27
	v_ashrrev_i32_e32 v27, 31, v26
	v_lshlrev_b64 v[26:27], 11, v[26:27]
	v_cvt_pk_bf16_f32 v25, v25, v21
	v_lshl_add_u64 v[26:27], v[74:75], 0, v[26:27]
	global_store_dwordx4 v[26:27], v[22:25], off sc1
	s_nop 1
	s_waitcnt lgkmcnt(0)
	s_cmp_lg_u32 s32, 0
	s_cbranch_scc1 .Lcv_loop
